# GEMM2 epilogue hand-written: gate and partial loads 4 row groups ahead with counted waits
# baseline (speedup 1.0000x reference)
; __device__ __forceinline__ u32x4 pack8(const float* v) { u32x4 o; o[0] = pk2(v[0], v[1]); o[1] = pk2(v[2], v[3]); o[2] = pk2(v[4], v[5]); o[3] = pk2(v[6], v[7]); return o; }
; #define E2_LOAD(g_, B_) do { const size_t off_ = (size_t)(row0 + ((g_) >> 2) * 128 + ((g_) & 3) * 16) * 2048 + col0; \
;             gb[B_][0] = *(const u32x4*)(G + off_); gb[B_][1] = *(const u32x4*)(G + off_ + 128); \
;             if (second) { pb[B_][0] = *(const u32x4*)(OUT + off_); pb[B_][1] = *(const u32x4*)(OUT + off_ + 128); } } while (0)
;     __device__ __forceinline__ void operator()(const AccT& acc, const pg8::Unit& u, int wr, int wc, int fr, int fq) const {
;         const int row0 = u.pm * 256 + wr * 64 + fr, col0 = u.pn * 256 + wc * 32 + 8 * fq;
;         const bf16_t* G = u.half ? MB : MA; const bool second = u.half != 0;
;         u32x4 gb[2][2], pb[2][2];
;     ...
;         E2_LOAD(0, 0);
; #pragma unroll
;         for (int g = 0; g < 8; ++g) {
;             const int ai = g >> 2, m = g & 3, B = g & 1;
;             if (g + 1 < 8) E2_LOAD(g + 1, B ^ 1);
;             const size_t off = (size_t)(row0 + ai * 128 + m * 16) * 2048 + col0;
; #pragma unroll
;             for (int bj = 0; bj < 2; ++bj) {
;                 float b[8], v[8]; unpack8(gb[B][bj], b);
; #pragma unroll
;                 for (int j = 0; j < 4; ++j) { v[j] = acc[ai][bj][m][0][j] * b[j]; v[4 + j] = acc[ai][bj][m][1][j] * b[4 + j]; }
;                 if (second) { float pr[8]; unpack8(pb[B][bj], pr);
; #pragma unroll
;                     for (int j = 0; j < 8; ++j) v[j] += pr[j]; }
;                 *(u32x4*)(OUT + off + bj * 128) = pack8(v);
;             }
.LBB0_38:
	v_readlane_b32 s28, v246, 52
	v_readlane_b32 s29, v246, 53
	s_cmp_eq_u32 s47, 0
	s_mov_b32 s6, 0x2c600000
	s_cselect_b32 s6, s6, 0x34700000
	s_add_u32 s28, s28, s6
	s_addc_u32 s29, s29, 0
	v_lshl_add_u32 v238, s49, 8, v187
	v_lshl_or_b32 v239, s48, 8, v192
	v_lshl_add_u32 v236, v238, 11, v239
	v_lshlrev_b32_e32 v236, 1, v236
	v_mov_b32_e32 v237, 0
	v_lshl_add_u64 v[176:177], s[28:29], 0, v[236:237]
	v_lshl_add_u64 v[190:191], s[10:11], 0, v[236:237]
	v_mov_b64_e32 v[202:203], v[190:191]
	s_mov_b64 s[28:29], 0x10000
	s_mov_b64 s[30:31], 0x50000
	s_cmp_lg_u32 s47, 0
	s_cbranch_scc1 .Le2_second
	global_load_dwordx4 v[64:67], v[176:177], off
	global_load_dwordx4 v[76:79], v[176:177], off offset:256
	v_lshl_add_u64 v[176:177], v[176:177], 0, s[28:29]
	global_load_dwordx4 v[146:149], v[176:177], off
	global_load_dwordx4 v[150:153], v[176:177], off offset:256
	v_lshl_add_u64 v[176:177], v[176:177], 0, s[28:29]
	global_load_dwordx4 v[172:175], v[176:177], off
	global_load_dwordx4 v[194:197], v[176:177], off offset:256
	v_lshl_add_u64 v[176:177], v[176:177], 0, s[28:29]
	global_load_dwordx4 v[220:223], v[176:177], off
	global_load_dwordx4 v[224:227], v[176:177], off offset:256
	v_lshl_add_u64 v[176:177], v[176:177], 0, s[30:31]
	s_waitcnt vmcnt(6)
	v_lshlrev_b32_e32 v236, 16, v64
	v_and_b32_e32 v237, 0xffff0000, v64
	v_pk_mul_f32 v[142:143], v[142:143], v[236:237]
	v_lshlrev_b32_e32 v238, 16, v65
	v_and_b32_e32 v239, 0xffff0000, v65
	v_pk_mul_f32 v[144:145], v[144:145], v[238:239]
	v_lshlrev_b32_e32 v236, 16, v66
	v_and_b32_e32 v237, 0xffff0000, v66
	v_pk_mul_f32 v[138:139], v[138:139], v[236:237]
	v_lshlrev_b32_e32 v238, 16, v67
	v_and_b32_e32 v239, 0xffff0000, v67
	v_pk_mul_f32 v[140:141], v[140:141], v[238:239]
	v_cvt_pk_bf16_f32 v64, v142, v143
	v_cvt_pk_bf16_f32 v65, v144, v145
	v_cvt_pk_bf16_f32 v66, v138, v139
	v_cvt_pk_bf16_f32 v67, v140, v141
	global_store_dwordx4 v[202:203], v[64:67], off
	v_lshlrev_b32_e32 v236, 16, v76
	v_and_b32_e32 v237, 0xffff0000, v76
	v_pk_mul_f32 v[132:133], v[132:133], v[236:237]
	v_lshlrev_b32_e32 v238, 16, v77
	v_and_b32_e32 v239, 0xffff0000, v77
	v_pk_mul_f32 v[134:135], v[134:135], v[238:239]
	v_lshlrev_b32_e32 v236, 16, v78
	v_and_b32_e32 v237, 0xffff0000, v78
	v_pk_mul_f32 v[128:129], v[128:129], v[236:237]
	v_lshlrev_b32_e32 v238, 16, v79
	v_and_b32_e32 v239, 0xffff0000, v79
	v_pk_mul_f32 v[130:131], v[130:131], v[238:239]
	v_cvt_pk_bf16_f32 v76, v132, v133
	v_cvt_pk_bf16_f32 v77, v134, v135
	v_cvt_pk_bf16_f32 v78, v128, v129
	v_cvt_pk_bf16_f32 v79, v130, v131
	global_store_dwordx4 v[202:203], v[76:79], off offset:256
	v_lshl_add_u64 v[202:203], v[202:203], 0, s[28:29]
	global_load_dwordx4 v[64:67], v[176:177], off
	global_load_dwordx4 v[76:79], v[176:177], off offset:256
	v_lshl_add_u64 v[176:177], v[176:177], 0, s[28:29]
	s_waitcnt vmcnt(8)
	v_lshlrev_b32_e32 v236, 16, v146
	v_and_b32_e32 v237, 0xffff0000, v146
	v_pk_mul_f32 v[124:125], v[124:125], v[236:237]
	v_lshlrev_b32_e32 v238, 16, v147
	v_and_b32_e32 v239, 0xffff0000, v147
	v_pk_mul_f32 v[126:127], v[126:127], v[238:239]
	v_lshlrev_b32_e32 v236, 16, v148
	v_and_b32_e32 v237, 0xffff0000, v148
	v_pk_mul_f32 v[120:121], v[120:121], v[236:237]
	v_lshlrev_b32_e32 v238, 16, v149
	v_and_b32_e32 v239, 0xffff0000, v149
	v_pk_mul_f32 v[122:123], v[122:123], v[238:239]
	v_cvt_pk_bf16_f32 v146, v124, v125
	v_cvt_pk_bf16_f32 v147, v126, v127
	v_cvt_pk_bf16_f32 v148, v120, v121
	v_cvt_pk_bf16_f32 v149, v122, v123
	global_store_dwordx4 v[202:203], v[146:149], off
	v_lshlrev_b32_e32 v236, 16, v150
	v_and_b32_e32 v237, 0xffff0000, v150
	v_pk_mul_f32 v[116:117], v[116:117], v[236:237]
	v_lshlrev_b32_e32 v238, 16, v151
	v_and_b32_e32 v239, 0xffff0000, v151
	v_pk_mul_f32 v[118:119], v[118:119], v[238:239]
	v_lshlrev_b32_e32 v236, 16, v152
	v_and_b32_e32 v237, 0xffff0000, v152
	v_pk_mul_f32 v[112:113], v[112:113], v[236:237]
	v_lshlrev_b32_e32 v238, 16, v153
	v_and_b32_e32 v239, 0xffff0000, v153
	v_pk_mul_f32 v[114:115], v[114:115], v[238:239]
	v_cvt_pk_bf16_f32 v150, v116, v117
	v_cvt_pk_bf16_f32 v151, v118, v119
	v_cvt_pk_bf16_f32 v152, v112, v113
	v_cvt_pk_bf16_f32 v153, v114, v115
	global_store_dwordx4 v[202:203], v[150:153], off offset:256
	v_lshl_add_u64 v[202:203], v[202:203], 0, s[28:29]
	global_load_dwordx4 v[146:149], v[176:177], off
	global_load_dwordx4 v[150:153], v[176:177], off offset:256
	v_lshl_add_u64 v[176:177], v[176:177], 0, s[28:29]
	s_waitcnt vmcnt(10)
	v_lshlrev_b32_e32 v236, 16, v172
	v_and_b32_e32 v237, 0xffff0000, v172
	v_pk_mul_f32 v[108:109], v[108:109], v[236:237]
	v_lshlrev_b32_e32 v238, 16, v173
	v_and_b32_e32 v239, 0xffff0000, v173
	v_pk_mul_f32 v[110:111], v[110:111], v[238:239]
	v_lshlrev_b32_e32 v236, 16, v174
	v_and_b32_e32 v237, 0xffff0000, v174
	v_pk_mul_f32 v[104:105], v[104:105], v[236:237]
	v_lshlrev_b32_e32 v238, 16, v175
	v_and_b32_e32 v239, 0xffff0000, v175
	v_pk_mul_f32 v[106:107], v[106:107], v[238:239]
	v_cvt_pk_bf16_f32 v172, v108, v109
	v_cvt_pk_bf16_f32 v173, v110, v111
	v_cvt_pk_bf16_f32 v174, v104, v105
	v_cvt_pk_bf16_f32 v175, v106, v107
	global_store_dwordx4 v[202:203], v[172:175], off
	v_lshlrev_b32_e32 v236, 16, v194
	v_and_b32_e32 v237, 0xffff0000, v194
	v_pk_mul_f32 v[96:97], v[96:97], v[236:237]
	v_lshlrev_b32_e32 v238, 16, v195
	v_and_b32_e32 v239, 0xffff0000, v195
	v_pk_mul_f32 v[98:99], v[98:99], v[238:239]
	v_lshlrev_b32_e32 v236, 16, v196
	v_and_b32_e32 v237, 0xffff0000, v196
	v_pk_mul_f32 v[92:93], v[92:93], v[236:237]
	v_lshlrev_b32_e32 v238, 16, v197
	v_and_b32_e32 v239, 0xffff0000, v197
	v_pk_mul_f32 v[94:95], v[94:95], v[238:239]
	v_cvt_pk_bf16_f32 v194, v96, v97
	v_cvt_pk_bf16_f32 v195, v98, v99
	v_cvt_pk_bf16_f32 v196, v92, v93
	v_cvt_pk_bf16_f32 v197, v94, v95
	global_store_dwordx4 v[202:203], v[194:197], off offset:256
	v_lshl_add_u64 v[202:203], v[202:203], 0, s[28:29]
	global_load_dwordx4 v[172:175], v[176:177], off
	global_load_dwordx4 v[194:197], v[176:177], off offset:256
	v_lshl_add_u64 v[176:177], v[176:177], 0, s[28:29]
	s_waitcnt vmcnt(12)
; __device__ __forceinline__ u32x4 pack8(const float* v) { u32x4 o; o[0] = pk2(v[0], v[1]); o[1] = pk2(v[2], v[3]); o[2] = pk2(v[4], v[5]); o[3] = pk2(v[6], v[7]); return o; }
; #define E2_LOAD(g_, B_) do { const size_t off_ = (size_t)(row0 + ((g_) >> 2) * 128 + ((g_) & 3) * 16) * 2048 + col0; \
;             gb[B_][0] = *(const u32x4*)(G + off_); gb[B_][1] = *(const u32x4*)(G + off_ + 128); \
;             if (second) { pb[B_][0] = *(const u32x4*)(OUT + off_); pb[B_][1] = *(const u32x4*)(OUT + off_ + 128); } } while (0)
;     __device__ __forceinline__ void operator()(const AccT& acc, const pg8::Unit& u, int wr, int wc, int fr, int fq) const {
;     ...
;         for (int g = 0; g < 8; ++g) {
;             const int ai = g >> 2, m = g & 3, B = g & 1;
;             if (g + 1 < 8) E2_LOAD(g + 1, B ^ 1);
;             const size_t off = (size_t)(row0 + ai * 128 + m * 16) * 2048 + col0;
; #pragma unroll
;             for (int bj = 0; bj < 2; ++bj) {
;                 float b[8], v[8]; unpack8(gb[B][bj], b);
; #pragma unroll
;                 for (int j = 0; j < 4; ++j) { v[j] = acc[ai][bj][m][0][j] * b[j]; v[4 + j] = acc[ai][bj][m][1][j] * b[4 + j]; }
;                 if (second) { float pr[8]; unpack8(pb[B][bj], pr);
; #pragma unroll
;                     for (int j = 0; j < 8; ++j) v[j] += pr[j]; }
;                 *(u32x4*)(OUT + off + bj * 128) = pack8(v);
;             }
	v_lshlrev_b32_e32 v236, 16, v220
	v_and_b32_e32 v237, 0xffff0000, v220
	v_pk_mul_f32 v[84:85], v[84:85], v[236:237]
	v_lshlrev_b32_e32 v238, 16, v221
	v_and_b32_e32 v239, 0xffff0000, v221
	v_pk_mul_f32 v[86:87], v[86:87], v[238:239]
	v_lshlrev_b32_e32 v236, 16, v222
	v_and_b32_e32 v237, 0xffff0000, v222
	v_pk_mul_f32 v[80:81], v[80:81], v[236:237]
	v_lshlrev_b32_e32 v238, 16, v223
	v_and_b32_e32 v239, 0xffff0000, v223
	v_pk_mul_f32 v[82:83], v[82:83], v[238:239]
	v_cvt_pk_bf16_f32 v220, v84, v85
	v_cvt_pk_bf16_f32 v221, v86, v87
	v_cvt_pk_bf16_f32 v222, v80, v81
	v_cvt_pk_bf16_f32 v223, v82, v83
	global_store_dwordx4 v[202:203], v[220:223], off
	v_lshlrev_b32_e32 v236, 16, v224
	v_and_b32_e32 v237, 0xffff0000, v224
	v_pk_mul_f32 v[72:73], v[72:73], v[236:237]
	v_lshlrev_b32_e32 v238, 16, v225
	v_and_b32_e32 v239, 0xffff0000, v225
	v_pk_mul_f32 v[74:75], v[74:75], v[238:239]
	v_lshlrev_b32_e32 v236, 16, v226
	v_and_b32_e32 v237, 0xffff0000, v226
	v_pk_mul_f32 v[68:69], v[68:69], v[236:237]
	v_lshlrev_b32_e32 v238, 16, v227
	v_and_b32_e32 v239, 0xffff0000, v227
	v_pk_mul_f32 v[70:71], v[70:71], v[238:239]
	v_cvt_pk_bf16_f32 v224, v72, v73
	v_cvt_pk_bf16_f32 v225, v74, v75
	v_cvt_pk_bf16_f32 v226, v68, v69
	v_cvt_pk_bf16_f32 v227, v70, v71
	global_store_dwordx4 v[202:203], v[224:227], off offset:256
	v_lshl_add_u64 v[202:203], v[202:203], 0, s[30:31]
	global_load_dwordx4 v[220:223], v[176:177], off
	global_load_dwordx4 v[224:227], v[176:177], off offset:256
	s_waitcnt vmcnt(12)
	v_lshlrev_b32_e32 v236, 16, v64
	v_and_b32_e32 v237, 0xffff0000, v64
	v_pk_mul_f32 v[60:61], v[60:61], v[236:237]
	v_lshlrev_b32_e32 v238, 16, v65
	v_and_b32_e32 v239, 0xffff0000, v65
	v_pk_mul_f32 v[62:63], v[62:63], v[238:239]
	v_lshlrev_b32_e32 v236, 16, v66
	v_and_b32_e32 v237, 0xffff0000, v66
	v_pk_mul_f32 v[56:57], v[56:57], v[236:237]
	v_lshlrev_b32_e32 v238, 16, v67
	v_and_b32_e32 v239, 0xffff0000, v67
	v_pk_mul_f32 v[58:59], v[58:59], v[238:239]
	v_cvt_pk_bf16_f32 v64, v60, v61
	v_cvt_pk_bf16_f32 v65, v62, v63
	v_cvt_pk_bf16_f32 v66, v56, v57
	v_cvt_pk_bf16_f32 v67, v58, v59
	global_store_dwordx4 v[202:203], v[64:67], off
	v_lshlrev_b32_e32 v236, 16, v76
	v_and_b32_e32 v237, 0xffff0000, v76
	v_pk_mul_f32 v[52:53], v[52:53], v[236:237]
	v_lshlrev_b32_e32 v238, 16, v77
	v_and_b32_e32 v239, 0xffff0000, v77
	v_pk_mul_f32 v[54:55], v[54:55], v[238:239]
	v_lshlrev_b32_e32 v236, 16, v78
	v_and_b32_e32 v237, 0xffff0000, v78
	v_pk_mul_f32 v[48:49], v[48:49], v[236:237]
	v_lshlrev_b32_e32 v238, 16, v79
	v_and_b32_e32 v239, 0xffff0000, v79
	v_pk_mul_f32 v[50:51], v[50:51], v[238:239]
	v_cvt_pk_bf16_f32 v76, v52, v53
	v_cvt_pk_bf16_f32 v77, v54, v55
	v_cvt_pk_bf16_f32 v78, v48, v49
	v_cvt_pk_bf16_f32 v79, v50, v51
	global_store_dwordx4 v[202:203], v[76:79], off offset:256
	v_lshl_add_u64 v[202:203], v[202:203], 0, s[28:29]
	s_waitcnt vmcnt(10)
	v_lshlrev_b32_e32 v236, 16, v146
	v_and_b32_e32 v237, 0xffff0000, v146
	v_pk_mul_f32 v[44:45], v[44:45], v[236:237]
	v_lshlrev_b32_e32 v238, 16, v147
	v_and_b32_e32 v239, 0xffff0000, v147
	v_pk_mul_f32 v[46:47], v[46:47], v[238:239]
	v_lshlrev_b32_e32 v236, 16, v148
	v_and_b32_e32 v237, 0xffff0000, v148
	v_pk_mul_f32 v[40:41], v[40:41], v[236:237]
	v_lshlrev_b32_e32 v238, 16, v149
	v_and_b32_e32 v239, 0xffff0000, v149
	v_pk_mul_f32 v[42:43], v[42:43], v[238:239]
	v_cvt_pk_bf16_f32 v146, v44, v45
	v_cvt_pk_bf16_f32 v147, v46, v47
	v_cvt_pk_bf16_f32 v148, v40, v41
	v_cvt_pk_bf16_f32 v149, v42, v43
	global_store_dwordx4 v[202:203], v[146:149], off
	v_lshlrev_b32_e32 v236, 16, v150
	v_and_b32_e32 v237, 0xffff0000, v150
	v_pk_mul_f32 v[36:37], v[36:37], v[236:237]
	v_lshlrev_b32_e32 v238, 16, v151
	v_and_b32_e32 v239, 0xffff0000, v151
	v_pk_mul_f32 v[38:39], v[38:39], v[238:239]
	v_lshlrev_b32_e32 v236, 16, v152
	v_and_b32_e32 v237, 0xffff0000, v152
	v_pk_mul_f32 v[32:33], v[32:33], v[236:237]
	v_lshlrev_b32_e32 v238, 16, v153
	v_and_b32_e32 v239, 0xffff0000, v153
	v_pk_mul_f32 v[34:35], v[34:35], v[238:239]
	v_cvt_pk_bf16_f32 v150, v36, v37
	v_cvt_pk_bf16_f32 v151, v38, v39
	v_cvt_pk_bf16_f32 v152, v32, v33
	v_cvt_pk_bf16_f32 v153, v34, v35
	global_store_dwordx4 v[202:203], v[150:153], off offset:256
	v_lshl_add_u64 v[202:203], v[202:203], 0, s[28:29]
	s_waitcnt vmcnt(8)
	v_lshlrev_b32_e32 v236, 16, v172
	v_and_b32_e32 v237, 0xffff0000, v172
	v_pk_mul_f32 v[28:29], v[28:29], v[236:237]
	v_lshlrev_b32_e32 v238, 16, v173
	v_and_b32_e32 v239, 0xffff0000, v173
	v_pk_mul_f32 v[30:31], v[30:31], v[238:239]
	v_lshlrev_b32_e32 v236, 16, v174
	v_and_b32_e32 v237, 0xffff0000, v174
	v_pk_mul_f32 v[24:25], v[24:25], v[236:237]
	v_lshlrev_b32_e32 v238, 16, v175
	v_and_b32_e32 v239, 0xffff0000, v175
	v_pk_mul_f32 v[26:27], v[26:27], v[238:239]
	v_cvt_pk_bf16_f32 v172, v28, v29
	v_cvt_pk_bf16_f32 v173, v30, v31
	v_cvt_pk_bf16_f32 v174, v24, v25
	v_cvt_pk_bf16_f32 v175, v26, v27
	global_store_dwordx4 v[202:203], v[172:175], off
	v_lshlrev_b32_e32 v236, 16, v194
	v_and_b32_e32 v237, 0xffff0000, v194
	v_pk_mul_f32 v[20:21], v[20:21], v[236:237]
	v_lshlrev_b32_e32 v238, 16, v195
	v_and_b32_e32 v239, 0xffff0000, v195
	v_pk_mul_f32 v[22:23], v[22:23], v[238:239]
	v_lshlrev_b32_e32 v236, 16, v196
	v_and_b32_e32 v237, 0xffff0000, v196
	v_pk_mul_f32 v[16:17], v[16:17], v[236:237]
	v_lshlrev_b32_e32 v238, 16, v197
	v_and_b32_e32 v239, 0xffff0000, v197
	v_pk_mul_f32 v[18:19], v[18:19], v[238:239]
	v_cvt_pk_bf16_f32 v194, v20, v21
	v_cvt_pk_bf16_f32 v195, v22, v23
	v_cvt_pk_bf16_f32 v196, v16, v17
	v_cvt_pk_bf16_f32 v197, v18, v19
	global_store_dwordx4 v[202:203], v[194:197], off offset:256
	v_lshl_add_u64 v[202:203], v[202:203], 0, s[28:29]
	s_waitcnt vmcnt(6)
	v_lshlrev_b32_e32 v236, 16, v220
	v_and_b32_e32 v237, 0xffff0000, v220
	v_pk_mul_f32 v[12:13], v[12:13], v[236:237]
	v_lshlrev_b32_e32 v238, 16, v221
	v_and_b32_e32 v239, 0xffff0000, v221
	v_pk_mul_f32 v[14:15], v[14:15], v[238:239]
	v_lshlrev_b32_e32 v236, 16, v222
	v_and_b32_e32 v237, 0xffff0000, v222
	v_pk_mul_f32 v[8:9], v[8:9], v[236:237]
	v_lshlrev_b32_e32 v238, 16, v223
	v_and_b32_e32 v239, 0xffff0000, v223
	v_pk_mul_f32 v[10:11], v[10:11], v[238:239]
	v_cvt_pk_bf16_f32 v220, v12, v13
	v_cvt_pk_bf16_f32 v221, v14, v15
	v_cvt_pk_bf16_f32 v222, v8, v9
	v_cvt_pk_bf16_f32 v223, v10, v11
	global_store_dwordx4 v[202:203], v[220:223], off
	v_lshlrev_b32_e32 v236, 16, v224
	v_and_b32_e32 v237, 0xffff0000, v224
	v_pk_mul_f32 v[4:5], v[4:5], v[236:237]
	v_lshlrev_b32_e32 v238, 16, v225
	v_and_b32_e32 v239, 0xffff0000, v225
	v_pk_mul_f32 v[6:7], v[6:7], v[238:239]
	v_lshlrev_b32_e32 v236, 16, v226
	v_and_b32_e32 v237, 0xffff0000, v226
	v_pk_mul_f32 v[0:1], v[0:1], v[236:237]
	v_lshlrev_b32_e32 v238, 16, v227
	v_and_b32_e32 v239, 0xffff0000, v227
	v_pk_mul_f32 v[2:3], v[2:3], v[238:239]
	v_cvt_pk_bf16_f32 v224, v4, v5
	v_cvt_pk_bf16_f32 v225, v6, v7
	v_cvt_pk_bf16_f32 v226, v0, v1
	v_cvt_pk_bf16_f32 v227, v2, v3
	global_store_dwordx4 v[202:203], v[224:227], off offset:256
	s_branch .Le2_done
; __device__ __forceinline__ u32x4 pack8(const float* v) { u32x4 o; o[0] = pk2(v[0], v[1]); o[1] = pk2(v[2], v[3]); o[2] = pk2(v[4], v[5]); o[3] = pk2(v[6], v[7]); return o; }
; #define E2_LOAD(g_, B_) do { const size_t off_ = (size_t)(row0 + ((g_) >> 2) * 128 + ((g_) & 3) * 16) * 2048 + col0; \
;             gb[B_][0] = *(const u32x4*)(G + off_); gb[B_][1] = *(const u32x4*)(G + off_ + 128); \
;             if (second) { pb[B_][0] = *(const u32x4*)(OUT + off_); pb[B_][1] = *(const u32x4*)(OUT + off_ + 128); } } while (0)
;     __device__ __forceinline__ void operator()(const AccT& acc, const pg8::Unit& u, int wr, int wc, int fr, int fq) const {
;     ...
;         const bf16_t* G = u.half ? MB : MA; const bool second = u.half != 0;
;         u32x4 gb[2][2], pb[2][2];
;     ...
;         E2_LOAD(0, 0);
; #pragma unroll
;         for (int g = 0; g < 8; ++g) {
;             const int ai = g >> 2, m = g & 3, B = g & 1;
;             if (g + 1 < 8) E2_LOAD(g + 1, B ^ 1);
;             const size_t off = (size_t)(row0 + ai * 128 + m * 16) * 2048 + col0;
; #pragma unroll
;             for (int bj = 0; bj < 2; ++bj) {
;                 float b[8], v[8]; unpack8(gb[B][bj], b);
; #pragma unroll
;                 for (int j = 0; j < 4; ++j) { v[j] = acc[ai][bj][m][0][j] * b[j]; v[4 + j] = acc[ai][bj][m][1][j] * b[4 + j]; }
;                 if (second) { float pr[8]; unpack8(pb[B][bj], pr);
; #pragma unroll
;                     for (int j = 0; j < 8; ++j) v[j] += pr[j]; }
;                 *(u32x4*)(OUT + off + bj * 128) = pack8(v);
;             }
.Le2_second:
	global_load_dwordx4 v[64:67], v[176:177], off
	global_load_dwordx4 v[76:79], v[176:177], off offset:256
	global_load_dwordx4 v[88:91], v[190:191], off
	global_load_dwordx4 v[100:103], v[190:191], off offset:256
	v_lshl_add_u64 v[176:177], v[176:177], 0, s[28:29]
	v_lshl_add_u64 v[190:191], v[190:191], 0, s[28:29]
	global_load_dwordx4 v[146:149], v[176:177], off
	global_load_dwordx4 v[150:153], v[176:177], off offset:256
	global_load_dwordx4 v[154:157], v[190:191], off
	global_load_dwordx4 v[158:161], v[190:191], off offset:256
	v_lshl_add_u64 v[176:177], v[176:177], 0, s[28:29]
	v_lshl_add_u64 v[190:191], v[190:191], 0, s[28:29]
	global_load_dwordx4 v[172:175], v[176:177], off
	global_load_dwordx4 v[194:197], v[176:177], off offset:256
	global_load_dwordx4 v[198:201], v[190:191], off
	global_load_dwordx4 v[216:219], v[190:191], off offset:256
	v_lshl_add_u64 v[176:177], v[176:177], 0, s[28:29]
	v_lshl_add_u64 v[190:191], v[190:191], 0, s[28:29]
	global_load_dwordx4 v[220:223], v[176:177], off
	global_load_dwordx4 v[224:227], v[176:177], off offset:256
	global_load_dwordx4 v[228:231], v[190:191], off
	global_load_dwordx4 v[232:235], v[190:191], off offset:256
	v_lshl_add_u64 v[176:177], v[176:177], 0, s[30:31]
	v_lshl_add_u64 v[190:191], v[190:191], 0, s[30:31]
	s_waitcnt vmcnt(12)
	v_lshlrev_b32_e32 v236, 16, v64
	v_and_b32_e32 v237, 0xffff0000, v64
	v_pk_mul_f32 v[142:143], v[142:143], v[236:237]
	v_lshlrev_b32_e32 v238, 16, v65
	v_and_b32_e32 v239, 0xffff0000, v65
	v_pk_mul_f32 v[144:145], v[144:145], v[238:239]
	v_lshlrev_b32_e32 v236, 16, v66
	v_and_b32_e32 v237, 0xffff0000, v66
	v_pk_mul_f32 v[138:139], v[138:139], v[236:237]
	v_lshlrev_b32_e32 v238, 16, v67
	v_and_b32_e32 v239, 0xffff0000, v67
	v_pk_mul_f32 v[140:141], v[140:141], v[238:239]
	v_lshlrev_b32_e32 v236, 16, v88
	v_and_b32_e32 v237, 0xffff0000, v88
	v_pk_add_f32 v[142:143], v[142:143], v[236:237]
	v_lshlrev_b32_e32 v238, 16, v89
	v_and_b32_e32 v239, 0xffff0000, v89
	v_pk_add_f32 v[144:145], v[144:145], v[238:239]
	v_lshlrev_b32_e32 v236, 16, v90
	v_and_b32_e32 v237, 0xffff0000, v90
	v_pk_add_f32 v[138:139], v[138:139], v[236:237]
	v_lshlrev_b32_e32 v238, 16, v91
	v_and_b32_e32 v239, 0xffff0000, v91
	v_pk_add_f32 v[140:141], v[140:141], v[238:239]
	v_cvt_pk_bf16_f32 v64, v142, v143
	v_cvt_pk_bf16_f32 v65, v144, v145
	v_cvt_pk_bf16_f32 v66, v138, v139
	v_cvt_pk_bf16_f32 v67, v140, v141
	global_store_dwordx4 v[202:203], v[64:67], off
	v_lshlrev_b32_e32 v236, 16, v76
	v_and_b32_e32 v237, 0xffff0000, v76
	v_pk_mul_f32 v[132:133], v[132:133], v[236:237]
	v_lshlrev_b32_e32 v238, 16, v77
	v_and_b32_e32 v239, 0xffff0000, v77
	v_pk_mul_f32 v[134:135], v[134:135], v[238:239]
	v_lshlrev_b32_e32 v236, 16, v78
	v_and_b32_e32 v237, 0xffff0000, v78
	v_pk_mul_f32 v[128:129], v[128:129], v[236:237]
	v_lshlrev_b32_e32 v238, 16, v79
	v_and_b32_e32 v239, 0xffff0000, v79
	v_pk_mul_f32 v[130:131], v[130:131], v[238:239]
	v_lshlrev_b32_e32 v236, 16, v100
	v_and_b32_e32 v237, 0xffff0000, v100
	v_pk_add_f32 v[132:133], v[132:133], v[236:237]
	v_lshlrev_b32_e32 v238, 16, v101
	v_and_b32_e32 v239, 0xffff0000, v101
	v_pk_add_f32 v[134:135], v[134:135], v[238:239]
	v_lshlrev_b32_e32 v236, 16, v102
	v_and_b32_e32 v237, 0xffff0000, v102
	v_pk_add_f32 v[128:129], v[128:129], v[236:237]
	v_lshlrev_b32_e32 v238, 16, v103
	v_and_b32_e32 v239, 0xffff0000, v103
	v_pk_add_f32 v[130:131], v[130:131], v[238:239]
	v_cvt_pk_bf16_f32 v76, v132, v133
	v_cvt_pk_bf16_f32 v77, v134, v135
	v_cvt_pk_bf16_f32 v78, v128, v129
	v_cvt_pk_bf16_f32 v79, v130, v131
	global_store_dwordx4 v[202:203], v[76:79], off offset:256
	v_lshl_add_u64 v[202:203], v[202:203], 0, s[28:29]
	global_load_dwordx4 v[64:67], v[176:177], off
	global_load_dwordx4 v[76:79], v[176:177], off offset:256
	global_load_dwordx4 v[88:91], v[190:191], off
	global_load_dwordx4 v[100:103], v[190:191], off offset:256
	v_lshl_add_u64 v[176:177], v[176:177], 0, s[28:29]
	v_lshl_add_u64 v[190:191], v[190:191], 0, s[28:29]
	s_waitcnt vmcnt(14)
	v_lshlrev_b32_e32 v236, 16, v146
	v_and_b32_e32 v237, 0xffff0000, v146
	v_pk_mul_f32 v[124:125], v[124:125], v[236:237]
	v_lshlrev_b32_e32 v238, 16, v147
	v_and_b32_e32 v239, 0xffff0000, v147
	v_pk_mul_f32 v[126:127], v[126:127], v[238:239]
	v_lshlrev_b32_e32 v236, 16, v148
	v_and_b32_e32 v237, 0xffff0000, v148
	v_pk_mul_f32 v[120:121], v[120:121], v[236:237]
	v_lshlrev_b32_e32 v238, 16, v149
	v_and_b32_e32 v239, 0xffff0000, v149
	v_pk_mul_f32 v[122:123], v[122:123], v[238:239]
	v_lshlrev_b32_e32 v236, 16, v154
	v_and_b32_e32 v237, 0xffff0000, v154
	v_pk_add_f32 v[124:125], v[124:125], v[236:237]
	v_lshlrev_b32_e32 v238, 16, v155
	v_and_b32_e32 v239, 0xffff0000, v155
	v_pk_add_f32 v[126:127], v[126:127], v[238:239]
	v_lshlrev_b32_e32 v236, 16, v156
	v_and_b32_e32 v237, 0xffff0000, v156
	v_pk_add_f32 v[120:121], v[120:121], v[236:237]
	v_lshlrev_b32_e32 v238, 16, v157
	v_and_b32_e32 v239, 0xffff0000, v157
	v_pk_add_f32 v[122:123], v[122:123], v[238:239]
	v_cvt_pk_bf16_f32 v146, v124, v125
	v_cvt_pk_bf16_f32 v147, v126, v127
	v_cvt_pk_bf16_f32 v148, v120, v121
	v_cvt_pk_bf16_f32 v149, v122, v123
	global_store_dwordx4 v[202:203], v[146:149], off
	v_lshlrev_b32_e32 v236, 16, v150
	v_and_b32_e32 v237, 0xffff0000, v150
	v_pk_mul_f32 v[116:117], v[116:117], v[236:237]
	v_lshlrev_b32_e32 v238, 16, v151
	v_and_b32_e32 v239, 0xffff0000, v151
	v_pk_mul_f32 v[118:119], v[118:119], v[238:239]
	v_lshlrev_b32_e32 v236, 16, v152
	v_and_b32_e32 v237, 0xffff0000, v152
	v_pk_mul_f32 v[112:113], v[112:113], v[236:237]
	v_lshlrev_b32_e32 v238, 16, v153
	v_and_b32_e32 v239, 0xffff0000, v153
	v_pk_mul_f32 v[114:115], v[114:115], v[238:239]
	v_lshlrev_b32_e32 v236, 16, v158
	v_and_b32_e32 v237, 0xffff0000, v158
	v_pk_add_f32 v[116:117], v[116:117], v[236:237]
	v_lshlrev_b32_e32 v238, 16, v159
	v_and_b32_e32 v239, 0xffff0000, v159
	v_pk_add_f32 v[118:119], v[118:119], v[238:239]
	v_lshlrev_b32_e32 v236, 16, v160
	v_and_b32_e32 v237, 0xffff0000, v160
	v_pk_add_f32 v[112:113], v[112:113], v[236:237]
	v_lshlrev_b32_e32 v238, 16, v161
	v_and_b32_e32 v239, 0xffff0000, v161
	v_pk_add_f32 v[114:115], v[114:115], v[238:239]
	v_cvt_pk_bf16_f32 v150, v116, v117
	v_cvt_pk_bf16_f32 v151, v118, v119
	v_cvt_pk_bf16_f32 v152, v112, v113
	v_cvt_pk_bf16_f32 v153, v114, v115
	global_store_dwordx4 v[202:203], v[150:153], off offset:256
	v_lshl_add_u64 v[202:203], v[202:203], 0, s[28:29]
	global_load_dwordx4 v[146:149], v[176:177], off
	global_load_dwordx4 v[150:153], v[176:177], off offset:256
	global_load_dwordx4 v[154:157], v[190:191], off
	global_load_dwordx4 v[158:161], v[190:191], off offset:256
	v_lshl_add_u64 v[176:177], v[176:177], 0, s[28:29]
	v_lshl_add_u64 v[190:191], v[190:191], 0, s[28:29]
	s_waitcnt vmcnt(16)
; __device__ __forceinline__ u32x4 pack8(const float* v) { u32x4 o; o[0] = pk2(v[0], v[1]); o[1] = pk2(v[2], v[3]); o[2] = pk2(v[4], v[5]); o[3] = pk2(v[6], v[7]); return o; }
; #define E2_LOAD(g_, B_) do { const size_t off_ = (size_t)(row0 + ((g_) >> 2) * 128 + ((g_) & 3) * 16) * 2048 + col0; \
;             gb[B_][0] = *(const u32x4*)(G + off_); gb[B_][1] = *(const u32x4*)(G + off_ + 128); \
;             if (second) { pb[B_][0] = *(const u32x4*)(OUT + off_); pb[B_][1] = *(const u32x4*)(OUT + off_ + 128); } } while (0)
;     __device__ __forceinline__ void operator()(const AccT& acc, const pg8::Unit& u, int wr, int wc, int fr, int fq) const {
;     ...
;         for (int g = 0; g < 8; ++g) {
;             const int ai = g >> 2, m = g & 3, B = g & 1;
;             if (g + 1 < 8) E2_LOAD(g + 1, B ^ 1);
;             const size_t off = (size_t)(row0 + ai * 128 + m * 16) * 2048 + col0;
; #pragma unroll
;             for (int bj = 0; bj < 2; ++bj) {
;                 float b[8], v[8]; unpack8(gb[B][bj], b);
; #pragma unroll
;                 for (int j = 0; j < 4; ++j) { v[j] = acc[ai][bj][m][0][j] * b[j]; v[4 + j] = acc[ai][bj][m][1][j] * b[4 + j]; }
;                 if (second) { float pr[8]; unpack8(pb[B][bj], pr);
; #pragma unroll
;                     for (int j = 0; j < 8; ++j) v[j] += pr[j]; }
;                 *(u32x4*)(OUT + off + bj * 128) = pack8(v);
;             }
	v_lshlrev_b32_e32 v236, 16, v172
	v_and_b32_e32 v237, 0xffff0000, v172
	v_pk_mul_f32 v[108:109], v[108:109], v[236:237]
	v_lshlrev_b32_e32 v238, 16, v173
	v_and_b32_e32 v239, 0xffff0000, v173
	v_pk_mul_f32 v[110:111], v[110:111], v[238:239]
	v_lshlrev_b32_e32 v236, 16, v174
	v_and_b32_e32 v237, 0xffff0000, v174
	v_pk_mul_f32 v[104:105], v[104:105], v[236:237]
	v_lshlrev_b32_e32 v238, 16, v175
	v_and_b32_e32 v239, 0xffff0000, v175
	v_pk_mul_f32 v[106:107], v[106:107], v[238:239]
	v_lshlrev_b32_e32 v236, 16, v198
	v_and_b32_e32 v237, 0xffff0000, v198
	v_pk_add_f32 v[108:109], v[108:109], v[236:237]
	v_lshlrev_b32_e32 v238, 16, v199
	v_and_b32_e32 v239, 0xffff0000, v199
	v_pk_add_f32 v[110:111], v[110:111], v[238:239]
	v_lshlrev_b32_e32 v236, 16, v200
	v_and_b32_e32 v237, 0xffff0000, v200
	v_pk_add_f32 v[104:105], v[104:105], v[236:237]
	v_lshlrev_b32_e32 v238, 16, v201
	v_and_b32_e32 v239, 0xffff0000, v201
	v_pk_add_f32 v[106:107], v[106:107], v[238:239]
	v_cvt_pk_bf16_f32 v172, v108, v109
	v_cvt_pk_bf16_f32 v173, v110, v111
	v_cvt_pk_bf16_f32 v174, v104, v105
	v_cvt_pk_bf16_f32 v175, v106, v107
	global_store_dwordx4 v[202:203], v[172:175], off
	v_lshlrev_b32_e32 v236, 16, v194
	v_and_b32_e32 v237, 0xffff0000, v194
	v_pk_mul_f32 v[96:97], v[96:97], v[236:237]
	v_lshlrev_b32_e32 v238, 16, v195
	v_and_b32_e32 v239, 0xffff0000, v195
	v_pk_mul_f32 v[98:99], v[98:99], v[238:239]
	v_lshlrev_b32_e32 v236, 16, v196
	v_and_b32_e32 v237, 0xffff0000, v196
	v_pk_mul_f32 v[92:93], v[92:93], v[236:237]
	v_lshlrev_b32_e32 v238, 16, v197
	v_and_b32_e32 v239, 0xffff0000, v197
	v_pk_mul_f32 v[94:95], v[94:95], v[238:239]
	v_lshlrev_b32_e32 v236, 16, v216
	v_and_b32_e32 v237, 0xffff0000, v216
	v_pk_add_f32 v[96:97], v[96:97], v[236:237]
	v_lshlrev_b32_e32 v238, 16, v217
	v_and_b32_e32 v239, 0xffff0000, v217
	v_pk_add_f32 v[98:99], v[98:99], v[238:239]
	v_lshlrev_b32_e32 v236, 16, v218
	v_and_b32_e32 v237, 0xffff0000, v218
	v_pk_add_f32 v[92:93], v[92:93], v[236:237]
	v_lshlrev_b32_e32 v238, 16, v219
	v_and_b32_e32 v239, 0xffff0000, v219
	v_pk_add_f32 v[94:95], v[94:95], v[238:239]
	v_cvt_pk_bf16_f32 v194, v96, v97
	v_cvt_pk_bf16_f32 v195, v98, v99
	v_cvt_pk_bf16_f32 v196, v92, v93
	v_cvt_pk_bf16_f32 v197, v94, v95
	global_store_dwordx4 v[202:203], v[194:197], off offset:256
	v_lshl_add_u64 v[202:203], v[202:203], 0, s[28:29]
	global_load_dwordx4 v[172:175], v[176:177], off
	global_load_dwordx4 v[194:197], v[176:177], off offset:256
	global_load_dwordx4 v[198:201], v[190:191], off
	global_load_dwordx4 v[216:219], v[190:191], off offset:256
	v_lshl_add_u64 v[176:177], v[176:177], 0, s[28:29]
	v_lshl_add_u64 v[190:191], v[190:191], 0, s[28:29]
	s_waitcnt vmcnt(18)
	v_lshlrev_b32_e32 v236, 16, v220
	v_and_b32_e32 v237, 0xffff0000, v220
	v_pk_mul_f32 v[84:85], v[84:85], v[236:237]
	v_lshlrev_b32_e32 v238, 16, v221
	v_and_b32_e32 v239, 0xffff0000, v221
	v_pk_mul_f32 v[86:87], v[86:87], v[238:239]
	v_lshlrev_b32_e32 v236, 16, v222
	v_and_b32_e32 v237, 0xffff0000, v222
	v_pk_mul_f32 v[80:81], v[80:81], v[236:237]
	v_lshlrev_b32_e32 v238, 16, v223
	v_and_b32_e32 v239, 0xffff0000, v223
	v_pk_mul_f32 v[82:83], v[82:83], v[238:239]
	v_lshlrev_b32_e32 v236, 16, v228
	v_and_b32_e32 v237, 0xffff0000, v228
	v_pk_add_f32 v[84:85], v[84:85], v[236:237]
	v_lshlrev_b32_e32 v238, 16, v229
	v_and_b32_e32 v239, 0xffff0000, v229
	v_pk_add_f32 v[86:87], v[86:87], v[238:239]
	v_lshlrev_b32_e32 v236, 16, v230
	v_and_b32_e32 v237, 0xffff0000, v230
	v_pk_add_f32 v[80:81], v[80:81], v[236:237]
	v_lshlrev_b32_e32 v238, 16, v231
	v_and_b32_e32 v239, 0xffff0000, v231
	v_pk_add_f32 v[82:83], v[82:83], v[238:239]
	v_cvt_pk_bf16_f32 v220, v84, v85
	v_cvt_pk_bf16_f32 v221, v86, v87
	v_cvt_pk_bf16_f32 v222, v80, v81
	v_cvt_pk_bf16_f32 v223, v82, v83
	global_store_dwordx4 v[202:203], v[220:223], off
	v_lshlrev_b32_e32 v236, 16, v224
	v_and_b32_e32 v237, 0xffff0000, v224
	v_pk_mul_f32 v[72:73], v[72:73], v[236:237]
	v_lshlrev_b32_e32 v238, 16, v225
	v_and_b32_e32 v239, 0xffff0000, v225
	v_pk_mul_f32 v[74:75], v[74:75], v[238:239]
	v_lshlrev_b32_e32 v236, 16, v226
	v_and_b32_e32 v237, 0xffff0000, v226
	v_pk_mul_f32 v[68:69], v[68:69], v[236:237]
	v_lshlrev_b32_e32 v238, 16, v227
	v_and_b32_e32 v239, 0xffff0000, v227
	v_pk_mul_f32 v[70:71], v[70:71], v[238:239]
	v_lshlrev_b32_e32 v236, 16, v232
	v_and_b32_e32 v237, 0xffff0000, v232
	v_pk_add_f32 v[72:73], v[72:73], v[236:237]
	v_lshlrev_b32_e32 v238, 16, v233
	v_and_b32_e32 v239, 0xffff0000, v233
	v_pk_add_f32 v[74:75], v[74:75], v[238:239]
	v_lshlrev_b32_e32 v236, 16, v234
	v_and_b32_e32 v237, 0xffff0000, v234
	v_pk_add_f32 v[68:69], v[68:69], v[236:237]
	v_lshlrev_b32_e32 v238, 16, v235
	v_and_b32_e32 v239, 0xffff0000, v235
	v_pk_add_f32 v[70:71], v[70:71], v[238:239]
	v_cvt_pk_bf16_f32 v224, v72, v73
	v_cvt_pk_bf16_f32 v225, v74, v75
	v_cvt_pk_bf16_f32 v226, v68, v69
	v_cvt_pk_bf16_f32 v227, v70, v71
	global_store_dwordx4 v[202:203], v[224:227], off offset:256
	v_lshl_add_u64 v[202:203], v[202:203], 0, s[30:31]
	global_load_dwordx4 v[220:223], v[176:177], off
	global_load_dwordx4 v[224:227], v[176:177], off offset:256
	global_load_dwordx4 v[228:231], v[190:191], off
	global_load_dwordx4 v[232:235], v[190:191], off offset:256
	s_waitcnt vmcnt(18)
; __device__ __forceinline__ u32x4 pack8(const float* v) { u32x4 o; o[0] = pk2(v[0], v[1]); o[1] = pk2(v[2], v[3]); o[2] = pk2(v[4], v[5]); o[3] = pk2(v[6], v[7]); return o; }
; #define E2_LOAD(g_, B_) do { const size_t off_ = (size_t)(row0 + ((g_) >> 2) * 128 + ((g_) & 3) * 16) * 2048 + col0; \
;             gb[B_][0] = *(const u32x4*)(G + off_); gb[B_][1] = *(const u32x4*)(G + off_ + 128); \
;             if (second) { pb[B_][0] = *(const u32x4*)(OUT + off_); pb[B_][1] = *(const u32x4*)(OUT + off_ + 128); } } while (0)
;     __device__ __forceinline__ void operator()(const AccT& acc, const pg8::Unit& u, int wr, int wc, int fr, int fq) const {
;     ...
;         for (int g = 0; g < 8; ++g) {
;             const int ai = g >> 2, m = g & 3, B = g & 1;
;             if (g + 1 < 8) E2_LOAD(g + 1, B ^ 1);
;             const size_t off = (size_t)(row0 + ai * 128 + m * 16) * 2048 + col0;
; #pragma unroll
;             for (int bj = 0; bj < 2; ++bj) {
;                 float b[8], v[8]; unpack8(gb[B][bj], b);
; #pragma unroll
;                 for (int j = 0; j < 4; ++j) { v[j] = acc[ai][bj][m][0][j] * b[j]; v[4 + j] = acc[ai][bj][m][1][j] * b[4 + j]; }
;                 if (second) { float pr[8]; unpack8(pb[B][bj], pr);
; #pragma unroll
;                     for (int j = 0; j < 8; ++j) v[j] += pr[j]; }
;                 *(u32x4*)(OUT + off + bj * 128) = pack8(v);
;             }
	v_lshlrev_b32_e32 v236, 16, v64
	v_and_b32_e32 v237, 0xffff0000, v64
	v_pk_mul_f32 v[60:61], v[60:61], v[236:237]
	v_lshlrev_b32_e32 v238, 16, v65
	v_and_b32_e32 v239, 0xffff0000, v65
	v_pk_mul_f32 v[62:63], v[62:63], v[238:239]
	v_lshlrev_b32_e32 v236, 16, v66
	v_and_b32_e32 v237, 0xffff0000, v66
	v_pk_mul_f32 v[56:57], v[56:57], v[236:237]
	v_lshlrev_b32_e32 v238, 16, v67
	v_and_b32_e32 v239, 0xffff0000, v67
	v_pk_mul_f32 v[58:59], v[58:59], v[238:239]
	v_lshlrev_b32_e32 v236, 16, v88
	v_and_b32_e32 v237, 0xffff0000, v88
	v_pk_add_f32 v[60:61], v[60:61], v[236:237]
	v_lshlrev_b32_e32 v238, 16, v89
	v_and_b32_e32 v239, 0xffff0000, v89
	v_pk_add_f32 v[62:63], v[62:63], v[238:239]
	v_lshlrev_b32_e32 v236, 16, v90
	v_and_b32_e32 v237, 0xffff0000, v90
	v_pk_add_f32 v[56:57], v[56:57], v[236:237]
	v_lshlrev_b32_e32 v238, 16, v91
	v_and_b32_e32 v239, 0xffff0000, v91
	v_pk_add_f32 v[58:59], v[58:59], v[238:239]
	v_cvt_pk_bf16_f32 v64, v60, v61
	v_cvt_pk_bf16_f32 v65, v62, v63
	v_cvt_pk_bf16_f32 v66, v56, v57
	v_cvt_pk_bf16_f32 v67, v58, v59
	global_store_dwordx4 v[202:203], v[64:67], off
	v_lshlrev_b32_e32 v236, 16, v76
	v_and_b32_e32 v237, 0xffff0000, v76
	v_pk_mul_f32 v[52:53], v[52:53], v[236:237]
	v_lshlrev_b32_e32 v238, 16, v77
	v_and_b32_e32 v239, 0xffff0000, v77
	v_pk_mul_f32 v[54:55], v[54:55], v[238:239]
	v_lshlrev_b32_e32 v236, 16, v78
	v_and_b32_e32 v237, 0xffff0000, v78
	v_pk_mul_f32 v[48:49], v[48:49], v[236:237]
	v_lshlrev_b32_e32 v238, 16, v79
	v_and_b32_e32 v239, 0xffff0000, v79
	v_pk_mul_f32 v[50:51], v[50:51], v[238:239]
	v_lshlrev_b32_e32 v236, 16, v100
	v_and_b32_e32 v237, 0xffff0000, v100
	v_pk_add_f32 v[52:53], v[52:53], v[236:237]
	v_lshlrev_b32_e32 v238, 16, v101
	v_and_b32_e32 v239, 0xffff0000, v101
	v_pk_add_f32 v[54:55], v[54:55], v[238:239]
	v_lshlrev_b32_e32 v236, 16, v102
	v_and_b32_e32 v237, 0xffff0000, v102
	v_pk_add_f32 v[48:49], v[48:49], v[236:237]
	v_lshlrev_b32_e32 v238, 16, v103
	v_and_b32_e32 v239, 0xffff0000, v103
	v_pk_add_f32 v[50:51], v[50:51], v[238:239]
	v_cvt_pk_bf16_f32 v76, v52, v53
	v_cvt_pk_bf16_f32 v77, v54, v55
	v_cvt_pk_bf16_f32 v78, v48, v49
	v_cvt_pk_bf16_f32 v79, v50, v51
	global_store_dwordx4 v[202:203], v[76:79], off offset:256
	v_lshl_add_u64 v[202:203], v[202:203], 0, s[28:29]
	s_waitcnt vmcnt(14)
	v_lshlrev_b32_e32 v236, 16, v146
	v_and_b32_e32 v237, 0xffff0000, v146
	v_pk_mul_f32 v[44:45], v[44:45], v[236:237]
	v_lshlrev_b32_e32 v238, 16, v147
	v_and_b32_e32 v239, 0xffff0000, v147
	v_pk_mul_f32 v[46:47], v[46:47], v[238:239]
	v_lshlrev_b32_e32 v236, 16, v148
	v_and_b32_e32 v237, 0xffff0000, v148
	v_pk_mul_f32 v[40:41], v[40:41], v[236:237]
	v_lshlrev_b32_e32 v238, 16, v149
	v_and_b32_e32 v239, 0xffff0000, v149
	v_pk_mul_f32 v[42:43], v[42:43], v[238:239]
	v_lshlrev_b32_e32 v236, 16, v154
	v_and_b32_e32 v237, 0xffff0000, v154
	v_pk_add_f32 v[44:45], v[44:45], v[236:237]
	v_lshlrev_b32_e32 v238, 16, v155
	v_and_b32_e32 v239, 0xffff0000, v155
	v_pk_add_f32 v[46:47], v[46:47], v[238:239]
	v_lshlrev_b32_e32 v236, 16, v156
	v_and_b32_e32 v237, 0xffff0000, v156
	v_pk_add_f32 v[40:41], v[40:41], v[236:237]
	v_lshlrev_b32_e32 v238, 16, v157
	v_and_b32_e32 v239, 0xffff0000, v157
	v_pk_add_f32 v[42:43], v[42:43], v[238:239]
	v_cvt_pk_bf16_f32 v146, v44, v45
	v_cvt_pk_bf16_f32 v147, v46, v47
	v_cvt_pk_bf16_f32 v148, v40, v41
	v_cvt_pk_bf16_f32 v149, v42, v43
	global_store_dwordx4 v[202:203], v[146:149], off
	v_lshlrev_b32_e32 v236, 16, v150
	v_and_b32_e32 v237, 0xffff0000, v150
	v_pk_mul_f32 v[36:37], v[36:37], v[236:237]
	v_lshlrev_b32_e32 v238, 16, v151
	v_and_b32_e32 v239, 0xffff0000, v151
	v_pk_mul_f32 v[38:39], v[38:39], v[238:239]
	v_lshlrev_b32_e32 v236, 16, v152
	v_and_b32_e32 v237, 0xffff0000, v152
	v_pk_mul_f32 v[32:33], v[32:33], v[236:237]
	v_lshlrev_b32_e32 v238, 16, v153
	v_and_b32_e32 v239, 0xffff0000, v153
	v_pk_mul_f32 v[34:35], v[34:35], v[238:239]
	v_lshlrev_b32_e32 v236, 16, v158
	v_and_b32_e32 v237, 0xffff0000, v158
	v_pk_add_f32 v[36:37], v[36:37], v[236:237]
	v_lshlrev_b32_e32 v238, 16, v159
	v_and_b32_e32 v239, 0xffff0000, v159
	v_pk_add_f32 v[38:39], v[38:39], v[238:239]
	v_lshlrev_b32_e32 v236, 16, v160
	v_and_b32_e32 v237, 0xffff0000, v160
	v_pk_add_f32 v[32:33], v[32:33], v[236:237]
	v_lshlrev_b32_e32 v238, 16, v161
	v_and_b32_e32 v239, 0xffff0000, v161
	v_pk_add_f32 v[34:35], v[34:35], v[238:239]
	v_cvt_pk_bf16_f32 v150, v36, v37
	v_cvt_pk_bf16_f32 v151, v38, v39
	v_cvt_pk_bf16_f32 v152, v32, v33
	v_cvt_pk_bf16_f32 v153, v34, v35
	global_store_dwordx4 v[202:203], v[150:153], off offset:256
	v_lshl_add_u64 v[202:203], v[202:203], 0, s[28:29]
	s_waitcnt vmcnt(10)
; __device__ __forceinline__ u32x4 pack8(const float* v) { u32x4 o; o[0] = pk2(v[0], v[1]); o[1] = pk2(v[2], v[3]); o[2] = pk2(v[4], v[5]); o[3] = pk2(v[6], v[7]); return o; }
; #define PG8_BAR __builtin_amdgcn_s_barrier()
; #define E2_LOAD(g_, B_) do { const size_t off_ = (size_t)(row0 + ((g_) >> 2) * 128 + ((g_) & 3) * 16) * 2048 + col0; \
;             gb[B_][0] = *(const u32x4*)(G + off_); gb[B_][1] = *(const u32x4*)(G + off_ + 128); \
;             if (second) { pb[B_][0] = *(const u32x4*)(OUT + off_); pb[B_][1] = *(const u32x4*)(OUT + off_ + 128); } } while (0)
; template <class Epi>
; __device__ __forceinline__ void gemm_phase(LAS unsigned char* lds, const Gemm g, const StaticOrder& S, const Epi& E, const int tid) {
;     ...
;         if (wr == 0) PG8_BAR;
;         E(acc, cur, wr, wc, fr, fq);
;         if (!has_next) break;
; #pragma unroll
;         for (int a = 0; a < 2; ++a)
; #pragma unroll
;             for (int b = 0; b < 2; ++b)
; #pragma unroll
;                 for (int m = 0; m < 4; ++m)
; #pragma unroll
;                     for (int n = 0; n < 2; ++n) acc[a][b][m][n] = (f32x4){0.f, 0.f, 0.f, 0.f};
;         cur = nxt; cA = nA; cB = nB; ++ui;
;         if (wr == 1) PG8_BAR;
;     }
;     __device__ __forceinline__ void operator()(const AccT& acc, const pg8::Unit& u, int wr, int wc, int fr, int fq) const {
;     ...
;         for (int g = 0; g < 8; ++g) {
;             const int ai = g >> 2, m = g & 3, B = g & 1;
;             if (g + 1 < 8) E2_LOAD(g + 1, B ^ 1);
;             const size_t off = (size_t)(row0 + ai * 128 + m * 16) * 2048 + col0;
; #pragma unroll
;             for (int bj = 0; bj < 2; ++bj) {
;                 float b[8], v[8]; unpack8(gb[B][bj], b);
; #pragma unroll
;                 for (int j = 0; j < 4; ++j) { v[j] = acc[ai][bj][m][0][j] * b[j]; v[4 + j] = acc[ai][bj][m][1][j] * b[4 + j]; }
;                 if (second) { float pr[8]; unpack8(pb[B][bj], pr);
; #pragma unroll
;                     for (int j = 0; j < 8; ++j) v[j] += pr[j]; }
;                 *(u32x4*)(OUT + off + bj * 128) = pack8(v);
;             }
;         }
	v_lshlrev_b32_e32 v236, 16, v172
	v_and_b32_e32 v237, 0xffff0000, v172
	v_pk_mul_f32 v[28:29], v[28:29], v[236:237]
	v_lshlrev_b32_e32 v238, 16, v173
	v_and_b32_e32 v239, 0xffff0000, v173
	v_pk_mul_f32 v[30:31], v[30:31], v[238:239]
	v_lshlrev_b32_e32 v236, 16, v174
	v_and_b32_e32 v237, 0xffff0000, v174
	v_pk_mul_f32 v[24:25], v[24:25], v[236:237]
	v_lshlrev_b32_e32 v238, 16, v175
	v_and_b32_e32 v239, 0xffff0000, v175
	v_pk_mul_f32 v[26:27], v[26:27], v[238:239]
	v_lshlrev_b32_e32 v236, 16, v198
	v_and_b32_e32 v237, 0xffff0000, v198
	v_pk_add_f32 v[28:29], v[28:29], v[236:237]
	v_lshlrev_b32_e32 v238, 16, v199
	v_and_b32_e32 v239, 0xffff0000, v199
	v_pk_add_f32 v[30:31], v[30:31], v[238:239]
	v_lshlrev_b32_e32 v236, 16, v200
	v_and_b32_e32 v237, 0xffff0000, v200
	v_pk_add_f32 v[24:25], v[24:25], v[236:237]
	v_lshlrev_b32_e32 v238, 16, v201
	v_and_b32_e32 v239, 0xffff0000, v201
	v_pk_add_f32 v[26:27], v[26:27], v[238:239]
	v_cvt_pk_bf16_f32 v172, v28, v29
	v_cvt_pk_bf16_f32 v173, v30, v31
	v_cvt_pk_bf16_f32 v174, v24, v25
	v_cvt_pk_bf16_f32 v175, v26, v27
	global_store_dwordx4 v[202:203], v[172:175], off
	v_lshlrev_b32_e32 v236, 16, v194
	v_and_b32_e32 v237, 0xffff0000, v194
	v_pk_mul_f32 v[20:21], v[20:21], v[236:237]
	v_lshlrev_b32_e32 v238, 16, v195
	v_and_b32_e32 v239, 0xffff0000, v195
	v_pk_mul_f32 v[22:23], v[22:23], v[238:239]
	v_lshlrev_b32_e32 v236, 16, v196
	v_and_b32_e32 v237, 0xffff0000, v196
	v_pk_mul_f32 v[16:17], v[16:17], v[236:237]
	v_lshlrev_b32_e32 v238, 16, v197
	v_and_b32_e32 v239, 0xffff0000, v197
	v_pk_mul_f32 v[18:19], v[18:19], v[238:239]
	v_lshlrev_b32_e32 v236, 16, v216
	v_and_b32_e32 v237, 0xffff0000, v216
	v_pk_add_f32 v[20:21], v[20:21], v[236:237]
	v_lshlrev_b32_e32 v238, 16, v217
	v_and_b32_e32 v239, 0xffff0000, v217
	v_pk_add_f32 v[22:23], v[22:23], v[238:239]
	v_lshlrev_b32_e32 v236, 16, v218
	v_and_b32_e32 v237, 0xffff0000, v218
	v_pk_add_f32 v[16:17], v[16:17], v[236:237]
	v_lshlrev_b32_e32 v238, 16, v219
	v_and_b32_e32 v239, 0xffff0000, v219
	v_pk_add_f32 v[18:19], v[18:19], v[238:239]
	v_cvt_pk_bf16_f32 v194, v20, v21
	v_cvt_pk_bf16_f32 v195, v22, v23
	v_cvt_pk_bf16_f32 v196, v16, v17
	v_cvt_pk_bf16_f32 v197, v18, v19
	global_store_dwordx4 v[202:203], v[194:197], off offset:256
	v_lshl_add_u64 v[202:203], v[202:203], 0, s[28:29]
	s_waitcnt vmcnt(6)
	v_lshlrev_b32_e32 v236, 16, v220
	v_and_b32_e32 v237, 0xffff0000, v220
	v_pk_mul_f32 v[12:13], v[12:13], v[236:237]
	v_lshlrev_b32_e32 v238, 16, v221
	v_and_b32_e32 v239, 0xffff0000, v221
	v_pk_mul_f32 v[14:15], v[14:15], v[238:239]
	v_lshlrev_b32_e32 v236, 16, v222
	v_and_b32_e32 v237, 0xffff0000, v222
	v_pk_mul_f32 v[8:9], v[8:9], v[236:237]
	v_lshlrev_b32_e32 v238, 16, v223
	v_and_b32_e32 v239, 0xffff0000, v223
	v_pk_mul_f32 v[10:11], v[10:11], v[238:239]
	v_lshlrev_b32_e32 v236, 16, v228
	v_and_b32_e32 v237, 0xffff0000, v228
	v_pk_add_f32 v[12:13], v[12:13], v[236:237]
	v_lshlrev_b32_e32 v238, 16, v229
	v_and_b32_e32 v239, 0xffff0000, v229
	v_pk_add_f32 v[14:15], v[14:15], v[238:239]
	v_lshlrev_b32_e32 v236, 16, v230
	v_and_b32_e32 v237, 0xffff0000, v230
	v_pk_add_f32 v[8:9], v[8:9], v[236:237]
	v_lshlrev_b32_e32 v238, 16, v231
	v_and_b32_e32 v239, 0xffff0000, v231
	v_pk_add_f32 v[10:11], v[10:11], v[238:239]
	v_cvt_pk_bf16_f32 v220, v12, v13
	v_cvt_pk_bf16_f32 v221, v14, v15
	v_cvt_pk_bf16_f32 v222, v8, v9
	v_cvt_pk_bf16_f32 v223, v10, v11
	global_store_dwordx4 v[202:203], v[220:223], off
	v_lshlrev_b32_e32 v236, 16, v224
	v_and_b32_e32 v237, 0xffff0000, v224
	v_pk_mul_f32 v[4:5], v[4:5], v[236:237]
	v_lshlrev_b32_e32 v238, 16, v225
	v_and_b32_e32 v239, 0xffff0000, v225
	v_pk_mul_f32 v[6:7], v[6:7], v[238:239]
	v_lshlrev_b32_e32 v236, 16, v226
	v_and_b32_e32 v237, 0xffff0000, v226
	v_pk_mul_f32 v[0:1], v[0:1], v[236:237]
	v_lshlrev_b32_e32 v238, 16, v227
	v_and_b32_e32 v239, 0xffff0000, v227
	v_pk_mul_f32 v[2:3], v[2:3], v[238:239]
	v_lshlrev_b32_e32 v236, 16, v232
	v_and_b32_e32 v237, 0xffff0000, v232
	v_pk_add_f32 v[4:5], v[4:5], v[236:237]
	v_lshlrev_b32_e32 v238, 16, v233
	v_and_b32_e32 v239, 0xffff0000, v233
	v_pk_add_f32 v[6:7], v[6:7], v[238:239]
	v_lshlrev_b32_e32 v236, 16, v234
	v_and_b32_e32 v237, 0xffff0000, v234
	v_pk_add_f32 v[0:1], v[0:1], v[236:237]
	v_lshlrev_b32_e32 v238, 16, v235
	v_and_b32_e32 v239, 0xffff0000, v235
	v_pk_add_f32 v[2:3], v[2:3], v[238:239]
	v_cvt_pk_bf16_f32 v224, v4, v5
	v_cvt_pk_bf16_f32 v225, v6, v7
	v_cvt_pk_bf16_f32 v226, v0, v1
	v_cvt_pk_bf16_f32 v227, v2, v3
	global_store_dwordx4 v[202:203], v[224:227], off offset:256
.Le2_done:
	s_andn2_b64 vcc, exec, s[4:5]
	s_mov_b64 s[4:5], -1
	s_cbranch_vccnz .LBB0_27
	s_andn2_b64 vcc, exec, s[8:9]
	s_cbranch_vccnz .LBB0_26
	s_barrier
	s_branch .LBB0_26
